# gate-load chains in swa/moba_own epilogues issued together; lru_fix leftover chunks batched; final RMSNorm loop: gain loaded once, 8 row loads up front
# speedup vs baseline: 1.0245x; 1.0245x over previous
; __device__ __forceinline__ void lru_fix_item(const Ptrs& P, int it) {
;     ...
;     for (; cc < c; ++cc) { const size_t o = (size_t)(b * 64 + cc) * 1024 + c8 * 8;
;         const f32x4 a0 = *(const f32x4*)(P.CHA() + o), a1 = *(const f32x4*)(P.CHA() + o + 4), h0 = *(const f32x4*)(P.CHH() + o), h1 = *(const f32x4*)(P.CHH() + o + 4);
;         H0 = a0 * H0 + h0; H1 = a1 * H1 + h1; }
.LBB0_779:
	s_sub_u32 s83, s66, s65
	v_lshl_add_u64 v[20:21], v[12:13], 0, s[60:61]
	global_load_dwordx4 v[36:39], v[12:13], off
	global_load_dwordx4 v[40:43], v[12:13], off offset:16
	global_load_dwordx4 v[44:47], v[20:21], off
	global_load_dwordx4 v[48:51], v[20:21], off offset:16
	s_cmp_lt_u32 s83, 2
	s_cbranch_scc1 .Lfixt_i_l0
	v_lshl_add_u64 v[12:13], v[12:13], 0, s[62:63]
	v_lshl_add_u64 v[20:21], v[12:13], 0, s[60:61]
	global_load_dwordx4 v[52:55], v[12:13], off
	global_load_dwordx4 v[56:59], v[12:13], off offset:16
	global_load_dwordx4 v[60:63], v[20:21], off
	global_load_dwordx4 v[64:67], v[20:21], off offset:16
	s_cmp_lt_u32 s83, 3
	s_cbranch_scc1 .Lfixt_i_l0
	v_lshl_add_u64 v[12:13], v[12:13], 0, s[62:63]
	v_lshl_add_u64 v[20:21], v[12:13], 0, s[60:61]
	global_load_dwordx4 v[68:71], v[12:13], off
	global_load_dwordx4 v[72:75], v[12:13], off offset:16
	global_load_dwordx4 v[76:79], v[20:21], off
	global_load_dwordx4 v[80:83], v[20:21], off offset:16
	s_cmp_lt_u32 s83, 4
	s_cbranch_scc1 .Lfixt_i_l0
	v_lshl_add_u64 v[12:13], v[12:13], 0, s[62:63]
	v_lshl_add_u64 v[20:21], v[12:13], 0, s[60:61]
	global_load_dwordx4 v[84:87], v[12:13], off
	global_load_dwordx4 v[88:91], v[12:13], off offset:16
	global_load_dwordx4 v[92:95], v[20:21], off
	global_load_dwordx4 v[96:99], v[20:21], off offset:16
	s_cmp_lt_u32 s83, 5
	s_cbranch_scc1 .Lfixt_i_l0
	v_lshl_add_u64 v[12:13], v[12:13], 0, s[62:63]
	v_lshl_add_u64 v[20:21], v[12:13], 0, s[60:61]
	global_load_dwordx4 v[100:103], v[12:13], off
	global_load_dwordx4 v[104:107], v[12:13], off offset:16
	global_load_dwordx4 v[108:111], v[20:21], off
	global_load_dwordx4 v[112:115], v[20:21], off offset:16
	s_cmp_lt_u32 s83, 6
	s_cbranch_scc1 .Lfixt_i_l0
	v_lshl_add_u64 v[12:13], v[12:13], 0, s[62:63]
	v_lshl_add_u64 v[20:21], v[12:13], 0, s[60:61]
	global_load_dwordx4 v[116:119], v[12:13], off
	global_load_dwordx4 v[120:123], v[12:13], off offset:16
	global_load_dwordx4 v[124:127], v[20:21], off
	global_load_dwordx4 v[128:131], v[20:21], off offset:16
	s_cmp_lt_u32 s83, 7
	s_cbranch_scc1 .Lfixt_i_l0
	v_lshl_add_u64 v[12:13], v[12:13], 0, s[62:63]
	v_lshl_add_u64 v[20:21], v[12:13], 0, s[60:61]
	global_load_dwordx4 v[132:135], v[12:13], off
	global_load_dwordx4 v[136:139], v[12:13], off offset:16
	global_load_dwordx4 v[140:143], v[20:21], off
	global_load_dwordx4 v[144:147], v[20:21], off offset:16
.Lfixt_i_l0:
	s_waitcnt vmcnt(0)
	v_pk_fma_f32 v[6:7], v[6:7], v[38:39], v[46:47]
	v_pk_fma_f32 v[4:5], v[4:5], v[36:37], v[44:45]
	v_pk_fma_f32 v[10:11], v[10:11], v[42:43], v[50:51]
	v_pk_fma_f32 v[8:9], v[8:9], v[40:41], v[48:49]
	s_cmp_lt_u32 s83, 2
	s_cbranch_scc1 .Lfixt_d_l0
	v_pk_fma_f32 v[6:7], v[6:7], v[54:55], v[62:63]
	v_pk_fma_f32 v[4:5], v[4:5], v[52:53], v[60:61]
	v_pk_fma_f32 v[10:11], v[10:11], v[58:59], v[66:67]
	v_pk_fma_f32 v[8:9], v[8:9], v[56:57], v[64:65]
	s_cmp_lt_u32 s83, 3
	s_cbranch_scc1 .Lfixt_d_l0
	v_pk_fma_f32 v[6:7], v[6:7], v[70:71], v[78:79]
	v_pk_fma_f32 v[4:5], v[4:5], v[68:69], v[76:77]
	v_pk_fma_f32 v[10:11], v[10:11], v[74:75], v[82:83]
	v_pk_fma_f32 v[8:9], v[8:9], v[72:73], v[80:81]
	s_cmp_lt_u32 s83, 4
	s_cbranch_scc1 .Lfixt_d_l0
	v_pk_fma_f32 v[6:7], v[6:7], v[86:87], v[94:95]
	v_pk_fma_f32 v[4:5], v[4:5], v[84:85], v[92:93]
	v_pk_fma_f32 v[10:11], v[10:11], v[90:91], v[98:99]
	v_pk_fma_f32 v[8:9], v[8:9], v[88:89], v[96:97]
	s_cmp_lt_u32 s83, 5
	s_cbranch_scc1 .Lfixt_d_l0
	v_pk_fma_f32 v[6:7], v[6:7], v[102:103], v[110:111]
	v_pk_fma_f32 v[4:5], v[4:5], v[100:101], v[108:109]
	v_pk_fma_f32 v[10:11], v[10:11], v[106:107], v[114:115]
	v_pk_fma_f32 v[8:9], v[8:9], v[104:105], v[112:113]
	s_cmp_lt_u32 s83, 6
	s_cbranch_scc1 .Lfixt_d_l0
	v_pk_fma_f32 v[6:7], v[6:7], v[118:119], v[126:127]
	v_pk_fma_f32 v[4:5], v[4:5], v[116:117], v[124:125]
	v_pk_fma_f32 v[10:11], v[10:11], v[122:123], v[130:131]
	v_pk_fma_f32 v[8:9], v[8:9], v[120:121], v[128:129]
	s_cmp_lt_u32 s83, 7
	s_cbranch_scc1 .Lfixt_d_l0
	v_pk_fma_f32 v[6:7], v[6:7], v[134:135], v[142:143]
	v_pk_fma_f32 v[4:5], v[4:5], v[132:133], v[140:141]
	v_pk_fma_f32 v[10:11], v[10:11], v[138:139], v[146:147]
	v_pk_fma_f32 v[8:9], v[8:9], v[136:137], v[144:145]
.Lfixt_d_l0:
	s_mov_b32 s65, s66

; __device__ __forceinline__ float bf_lo(unsigned u) { return __uint_as_float(u << 16); }
; __device__ __forceinline__ float bf_hi(unsigned u) { return __uint_as_float(u & 0xffff0000u); }
; __device__ __forceinline__ void swa_item(LAS unsigned char* lds, const Ptrs& P, int l, int b, int hk, int qblk) {
;     ...
;         const float lt = lsum + __shfl_xor(lsum, 32) + __builtin_amdgcn_exp2f(sink2 - m); const float inv = __builtin_amdgcn_rcpf(lt);
; #pragma unroll
;         for (int dt = 0; dt < 2; ++dt)
; #pragma unroll
;             for (int g4 = 0; g4 < 4; ++g4) { const int d = 32 * dt + 8 * g4 + 4 * hi;
;                 const u32x2 gw = *(const u32x2*)(P.PA() + qrow * NA + C_GB + hq * 64 + d);
;                 const float i64 = inv * 16.f; int w8 = 0;
;                 w8 = __builtin_amdgcn_cvt_pk_fp8_f32(o[dt][4 * g4] * i64 * bf_lo(gw.x), o[dt][4 * g4 + 1] * i64 * bf_hi(gw.x), w8, false); w8 = __builtin_amdgcn_cvt_pk_fp8_f32(o[dt][4 * g4 + 2] * i64 * bf_lo(gw.y), o[dt][4 * g4 + 3] * i64 * bf_hi(gw.y), w8, true);
;                 *(unsigned*)(P.Y8() + qrow * 2048 + 1024 + hq * 64 + d) = (unsigned)w8; }
;     }
;     __syncthreads();
.LBB0_785:
	v_or_b32_e32 v0, s49, v133
	v_or_b32_e32 v6, s6, v0
	v_mov_b64_e32 v[0:1], s[14:15]
	v_mad_i64_i32 v[0:1], s[0:1], v6, s18, v[0:1]
	v_lshl_add_u64 v[2:3], s[24:25], 1, v[0:1]
	v_lshlrev_b32_e32 v4, 1, v96
	v_mov_b32_e32 v5, v97
	v_lshl_add_u64 v[2:3], v[2:3], 0, v[4:5]
	v_add_co_u32_e32 v4, vcc, s19, v2
	ds_bpermute_b32 v7, v130, v115
	s_nop 0
	v_addc_co_u32_e32 v5, vcc, 0, v3, vcc
	global_load_dwordx2 v[204:205], v[4:5], off offset:3072
	global_load_dwordx2 v[206:207], v[4:5], off offset:3088
	global_load_dwordx2 v[208:209], v[4:5], off offset:3104
	global_load_dwordx2 v[210:211], v[4:5], off offset:3120
	global_load_dwordx2 v[212:213], v[4:5], off offset:3136
	global_load_dwordx2 v[214:215], v[4:5], off offset:3152
	global_load_dwordx2 v[216:217], v[4:5], off offset:3168
	global_load_dwordx2 v[218:219], v[4:5], off offset:3184
	v_sub_f32_e32 v8, v114, v117
	v_exp_f32_e32 v8, v8
	v_mad_i64_i32 v[0:1], s[0:1], v6, s46, v[0:1]
	s_waitcnt lgkmcnt(0)
	v_add_f32_e32 v6, v115, v7
	v_add_f32_e32 v6, v8, v6
	v_rcp_f32_e32 v6, v6
	v_mov_b32_e32 v9, v97
	v_lshl_add_u64 v[0:1], v[0:1], 0, s[24:25]
	v_lshl_add_u64 v[0:1], v[0:1], 0, v[96:97]
	v_mul_f32_e32 v6, 0x41800000, v6
	v_mul_f32_e32 v7, v32, v6
	v_mul_f32_e32 v8, v33, v6
	v_mul_f32_e32 v10, v34, v6
	v_mul_f32_e32 v11, v35, v6
	v_lshl_add_u64 v[2:3], v[2:3], 0, s[20:21]
	s_add_i32 s38, s38, s33
	s_cmpk_lt_i32 s38, 0x200
	s_waitcnt vmcnt(7)
	v_lshlrev_b32_e32 v12, 16, v204
	v_and_b32_e32 v4, 0xffff0000, v204
	v_mul_f32_e32 v7, v7, v12
	v_mul_f32_e32 v4, v8, v4
	v_cvt_pk_fp8_f32 v9, v7, v4
	v_lshlrev_b32_e32 v13, 16, v205
	v_and_b32_e32 v4, 0xffff0000, v205
	v_mul_f32_e32 v5, v10, v13
	v_mul_f32_e32 v4, v11, v4
	v_cvt_pk_fp8_f32 v9, v5, v4 op_sel:[0,0,1]
	v_add_co_u32_e32 v4, vcc, s47, v0
	v_mul_f32_e32 v8, v36, v6
	s_nop 0
	v_addc_co_u32_e32 v5, vcc, 0, v1, vcc
	global_store_dword v[4:5], v9, off offset:1024
	v_mul_f32_e32 v9, v37, v6
	v_mov_b32_e32 v7, v97
	v_mul_f32_e32 v10, v38, v6
	v_mul_f32_e32 v11, v39, v6
	v_lshl_add_u64 v[0:1], v[0:1], 0, s[22:23]
	s_waitcnt vmcnt(7)
	v_lshlrev_b32_e32 v12, 16, v206
	v_and_b32_e32 v4, 0xffff0000, v206
	v_mul_f32_e32 v8, v8, v12
	v_mul_f32_e32 v4, v9, v4
	v_cvt_pk_fp8_f32 v7, v8, v4
	v_lshlrev_b32_e32 v13, 16, v207
	v_and_b32_e32 v4, 0xffff0000, v207
	v_mul_f32_e32 v5, v10, v13
	v_mul_f32_e32 v4, v11, v4
	v_cvt_pk_fp8_f32 v7, v5, v4 op_sel:[0,0,1]
	v_mul_f32_e32 v8, v40, v6
	v_mul_f32_e32 v9, v41, v6
	v_mul_f32_e32 v10, v42, v6
	global_store_dword v[0:1], v7, off offset:8
	v_mov_b32_e32 v7, v97
	v_mul_f32_e32 v11, v43, v6
	s_waitcnt vmcnt(7)
	v_lshlrev_b32_e32 v12, 16, v208
	v_and_b32_e32 v4, 0xffff0000, v208
	v_mul_f32_e32 v8, v8, v12
	v_mul_f32_e32 v4, v9, v4
	v_cvt_pk_fp8_f32 v7, v8, v4
	v_lshlrev_b32_e32 v13, 16, v209
	v_and_b32_e32 v4, 0xffff0000, v209
	v_mul_f32_e32 v5, v10, v13
	v_mul_f32_e32 v4, v11, v4
	v_cvt_pk_fp8_f32 v7, v5, v4 op_sel:[0,0,1]
	v_mul_f32_e32 v8, v44, v6
	v_mul_f32_e32 v9, v45, v6
	v_mul_f32_e32 v10, v46, v6
	global_store_dword v[0:1], v7, off offset:16
	v_mov_b32_e32 v7, v97
	v_mul_f32_e32 v11, v47, v6
	s_waitcnt vmcnt(7)
	v_lshlrev_b32_e32 v12, 16, v210
	v_and_b32_e32 v4, 0xffff0000, v210
	v_mul_f32_e32 v8, v8, v12
	v_mul_f32_e32 v4, v9, v4
	v_cvt_pk_fp8_f32 v7, v8, v4
	v_lshlrev_b32_e32 v13, 16, v211
	v_and_b32_e32 v4, 0xffff0000, v211
	v_mul_f32_e32 v5, v10, v13
	v_mul_f32_e32 v4, v11, v4
	v_cvt_pk_fp8_f32 v7, v5, v4 op_sel:[0,0,1]
	v_mul_f32_e32 v8, v16, v6
	v_mul_f32_e32 v9, v17, v6
	v_mul_f32_e32 v10, v18, v6
	global_store_dword v[0:1], v7, off offset:24
	v_mov_b32_e32 v7, v97
	v_mul_f32_e32 v11, v19, v6
	s_waitcnt vmcnt(7)
	v_lshlrev_b32_e32 v12, 16, v212
	v_and_b32_e32 v4, 0xffff0000, v212
	v_mul_f32_e32 v8, v8, v12
	v_mul_f32_e32 v4, v9, v4
	v_cvt_pk_fp8_f32 v7, v8, v4
	v_lshlrev_b32_e32 v13, 16, v213
	v_and_b32_e32 v4, 0xffff0000, v213
	v_mul_f32_e32 v5, v10, v13
	v_mul_f32_e32 v4, v11, v4
	v_cvt_pk_fp8_f32 v7, v5, v4 op_sel:[0,0,1]
	v_mul_f32_e32 v8, v20, v6
	v_mul_f32_e32 v9, v21, v6
	v_mul_f32_e32 v10, v22, v6
	global_store_dword v[0:1], v7, off offset:32
	v_mov_b32_e32 v7, v97
	v_mul_f32_e32 v11, v23, v6
	s_waitcnt vmcnt(7)
	v_lshlrev_b32_e32 v12, 16, v214
	v_and_b32_e32 v4, 0xffff0000, v214
	v_mul_f32_e32 v8, v8, v12
	v_mul_f32_e32 v4, v9, v4
	v_cvt_pk_fp8_f32 v7, v8, v4
	v_lshlrev_b32_e32 v13, 16, v215
	v_and_b32_e32 v4, 0xffff0000, v215
	v_mul_f32_e32 v5, v10, v13
	v_mul_f32_e32 v4, v11, v4
	v_cvt_pk_fp8_f32 v7, v5, v4 op_sel:[0,0,1]
	v_mul_f32_e32 v8, v24, v6
	v_mul_f32_e32 v9, v25, v6
	v_mul_f32_e32 v10, v26, v6
	global_store_dword v[0:1], v7, off offset:40
	v_mov_b32_e32 v7, v97
	v_mul_f32_e32 v11, v27, v6
	s_waitcnt vmcnt(7)
	v_lshlrev_b32_e32 v12, 16, v216
	v_and_b32_e32 v4, 0xffff0000, v216
	v_mul_f32_e32 v8, v8, v12
	v_mul_f32_e32 v4, v9, v4
	v_cvt_pk_fp8_f32 v7, v8, v4
	v_lshlrev_b32_e32 v13, 16, v217
	v_and_b32_e32 v4, 0xffff0000, v217
	v_mul_f32_e32 v5, v10, v13
	v_mul_f32_e32 v4, v11, v4
	v_cvt_pk_fp8_f32 v7, v5, v4 op_sel:[0,0,1]
	v_mul_f32_e32 v5, v28, v6
	v_mov_b32_e32 v4, v97
	v_mul_f32_e32 v8, v30, v6
	global_store_dword v[0:1], v7, off offset:48
	v_mul_f32_e32 v7, v29, v6
	v_mul_f32_e32 v6, v31, v6
	s_waitcnt vmcnt(7)
	v_lshlrev_b32_e32 v9, 16, v218
	v_and_b32_e32 v2, 0xffff0000, v218
	v_mul_f32_e32 v5, v5, v9
	v_mul_f32_e32 v2, v7, v2
	v_cvt_pk_fp8_f32 v4, v5, v2
	v_lshlrev_b32_e32 v10, 16, v219
	v_and_b32_e32 v2, 0xffff0000, v219
	v_mul_f32_e32 v3, v8, v10
	v_mul_f32_e32 v2, v6, v2
	v_cvt_pk_fp8_f32 v4, v3, v2 op_sel:[0,0,1]
	global_store_dword v[0:1], v4, off offset:56
	s_barrier
	s_cbranch_scc0 .LBB0_878

; __device__ __forceinline__ float bf_lo(unsigned u) { return __uint_as_float(u << 16); }
; __device__ __forceinline__ float bf_hi(unsigned u) { return __uint_as_float(u & 0xffff0000u); }
; __device__ __forceinline__ void swa_item(LAS unsigned char* lds, const Ptrs& P, int l, int b, int hk, int qblk) {
;     ...
;         const float lt = lsum + __shfl_xor(lsum, 32) + __builtin_amdgcn_exp2f(sink2 - m); const float inv = __builtin_amdgcn_rcpf(lt);
; #pragma unroll
;         for (int dt = 0; dt < 2; ++dt)
; #pragma unroll
;             for (int g4 = 0; g4 < 4; ++g4) { const int d = 32 * dt + 8 * g4 + 4 * hi;
;                 const u32x2 gw = *(const u32x2*)(P.PA() + qrow * NA + C_GB + hq * 64 + d);
;                 const float i64 = inv * 16.f; int w8 = 0;
;                 w8 = __builtin_amdgcn_cvt_pk_fp8_f32(o[dt][4 * g4] * i64 * bf_lo(gw.x), o[dt][4 * g4 + 1] * i64 * bf_hi(gw.x), w8, false); w8 = __builtin_amdgcn_cvt_pk_fp8_f32(o[dt][4 * g4 + 2] * i64 * bf_lo(gw.y), o[dt][4 * g4 + 3] * i64 * bf_hi(gw.y), w8, true);
;                 *(unsigned*)(P.Y8() + qrow * 2048 + 1024 + hq * 64 + d) = (unsigned)w8; }
.LBB0_841:
	v_or_b32_e32 v32, s53, v133
	v_or_b32_e32 v38, s6, v32
	v_mov_b64_e32 v[32:33], s[14:15]
	v_mad_i64_i32 v[32:33], s[0:1], v38, s18, v[32:33]
	v_lshl_add_u64 v[34:35], s[24:25], 1, v[32:33]
	v_lshlrev_b32_e32 v36, 1, v96
	v_mov_b32_e32 v37, v97
	v_lshl_add_u64 v[34:35], v[34:35], 0, v[36:37]
	v_add_co_u32_e32 v36, vcc, s19, v34
	ds_bpermute_b32 v39, v130, v140
	s_nop 0
	v_addc_co_u32_e32 v37, vcc, 0, v35, vcc
	global_load_dwordx2 v[220:221], v[36:37], off offset:3072
	global_load_dwordx2 v[222:223], v[36:37], off offset:3088
	global_load_dwordx2 v[224:225], v[36:37], off offset:3104
	global_load_dwordx2 v[226:227], v[36:37], off offset:3120
	global_load_dwordx2 v[228:229], v[36:37], off offset:3136
	global_load_dwordx2 v[230:231], v[36:37], off offset:3152
	global_load_dwordx2 v[232:233], v[36:37], off offset:3168
	global_load_dwordx2 v[234:235], v[36:37], off offset:3184
	v_fma_f32 v40, v138, s42, -v144
	v_exp_f32_e32 v40, v40
	v_mad_i64_i32 v[32:33], s[0:1], v38, s46, v[32:33]
	s_waitcnt lgkmcnt(0)
	v_add_f32_e32 v38, v140, v39
	v_add_f32_e32 v38, v40, v38
	v_rcp_f32_e32 v38, v38
	v_mov_b32_e32 v41, v97
	v_lshl_add_u64 v[32:33], v[32:33], 0, s[24:25]
	v_lshl_add_u64 v[32:33], v[32:33], 0, v[96:97]
	v_mul_f32_e32 v50, 0x41800000, v38
	v_mul_f32_e32 v16, v16, v50
	v_mul_f32_e32 v17, v17, v50
	v_mul_f32_e32 v18, v18, v50
	v_mul_f32_e32 v19, v19, v50
	v_lshl_add_u64 v[34:35], v[34:35], 0, s[20:21]
	v_lshl_add_u64 v[48:49], v[32:33], 0, s[22:23]
	v_mul_f32_e32 v0, v0, v50
	v_mul_f32_e32 v1, v1, v50
	v_mul_f32_e32 v2, v2, v50
	v_mul_f32_e32 v3, v3, v50
	v_mov_b32_e32 v115, 0
	v_mul_f32_e32 v114, 0x3fb8aa3b, v138
	v_subrev_u32_e32 v116, 27, v137
	v_mov_b32_e32 v40, v97
	v_mov_b32_e32 v42, v97
	v_mov_b32_e32 v43, v97
	v_mov_b32_e32 v44, v97
	v_mov_b32_e32 v45, v97
	v_mov_b32_e32 v46, v97
	v_mov_b32_e32 v47, v97
	v_mov_b32_e32 v117, 0xf149f2ca
	v_mov_b32_e32 v80, 0
	v_mov_b32_e32 v82, 0
	v_mov_b32_e32 v84, 0
	v_mov_b32_e32 v86, 0
	v_mov_b32_e32 v88, 0
	v_mov_b32_e32 v90, 0
	v_mov_b32_e32 v92, 0
	v_mov_b32_e32 v94, 0
	v_mov_b32_e32 v98, 0
	v_mov_b32_e32 v100, 0
	v_mov_b32_e32 v102, 0
	v_mov_b32_e32 v104, 0
	v_mov_b32_e32 v106, 0
	v_mov_b32_e32 v108, 0
	v_mov_b32_e32 v110, 0
	v_mov_b32_e32 v112, 0
	v_mov_b32_e32 v81, v115
	v_mov_b32_e32 v83, v115
	v_mov_b32_e32 v85, v115
	v_mov_b32_e32 v87, v115
	v_mov_b32_e32 v89, v115
	v_mov_b32_e32 v91, v115
	v_mov_b32_e32 v93, v115
	v_mov_b32_e32 v95, v115
	v_mov_b32_e32 v99, v115
	v_mov_b32_e32 v101, v115
	v_mov_b32_e32 v103, v115
	v_mov_b32_e32 v105, v115
	v_mov_b32_e32 v107, v115
	v_mov_b32_e32 v109, v115
	v_mov_b32_e32 v111, v115
	v_mov_b32_e32 v113, v115
	s_waitcnt vmcnt(7)
	v_lshlrev_b32_e32 v38, 16, v220
	v_and_b32_e32 v36, 0xffff0000, v220
	v_mul_f32_e32 v16, v16, v38
	v_mul_f32_e32 v17, v17, v36
	v_cvt_pk_fp8_f32 v41, v16, v17
	v_lshlrev_b32_e32 v39, 16, v221
	v_and_b32_e32 v16, 0xffff0000, v221
	v_mul_f32_e32 v17, v18, v39
	v_mul_f32_e32 v16, v19, v16
	v_cvt_pk_fp8_f32 v41, v17, v16 op_sel:[0,0,1]
	v_add_co_u32_e32 v16, vcc, s47, v32
	v_mul_f32_e32 v19, v20, v50
	s_nop 0
	v_addc_co_u32_e32 v17, vcc, 0, v33, vcc
	global_store_dword v[16:17], v41, off offset:1024
	v_mul_f32_e32 v20, v21, v50
	v_mul_f32_e32 v21, v22, v50
	v_mul_f32_e32 v22, v23, v50
	v_mov_b32_e32 v18, v97
	v_mov_b32_e32 v32, v97
	v_mov_b32_e32 v33, v97
	v_mov_b32_e32 v37, v97
	v_mov_b32_e32 v38, v97
	v_mov_b32_e32 v39, v97
	v_mov_b32_e32 v41, v97
	s_waitcnt vmcnt(7)
; __device__ __forceinline__ float bf_lo(unsigned u) { return __uint_as_float(u << 16); }
; __device__ __forceinline__ float bf_hi(unsigned u) { return __uint_as_float(u & 0xffff0000u); }
; __device__ __forceinline__ void swa_item(LAS unsigned char* lds, const Ptrs& P, int l, int b, int hk, int qblk) {
;     ...
;             for (int g4 = 0; g4 < 4; ++g4) { const int d = 32 * dt + 8 * g4 + 4 * hi;
;                 const u32x2 gw = *(const u32x2*)(P.PA() + qrow * NA + C_GB + hq * 64 + d);
;                 const float i64 = inv * 16.f; int w8 = 0;
;                 w8 = __builtin_amdgcn_cvt_pk_fp8_f32(o[dt][4 * g4] * i64 * bf_lo(gw.x), o[dt][4 * g4 + 1] * i64 * bf_hi(gw.x), w8, false); w8 = __builtin_amdgcn_cvt_pk_fp8_f32(o[dt][4 * g4 + 2] * i64 * bf_lo(gw.y), o[dt][4 * g4 + 3] * i64 * bf_hi(gw.y), w8, true);
;                 *(unsigned*)(P.Y8() + qrow * 2048 + 1024 + hq * 64 + d) = (unsigned)w8; }
	v_lshlrev_b32_e32 v23, 16, v222
	v_and_b32_e32 v16, 0xffff0000, v222
	v_mul_f32_e32 v19, v19, v23
	v_mul_f32_e32 v16, v20, v16
	v_cvt_pk_fp8_f32 v18, v19, v16
	v_lshlrev_b32_e32 v36, 16, v223
	v_and_b32_e32 v16, 0xffff0000, v223
	v_mul_f32_e32 v17, v21, v36
	v_mul_f32_e32 v16, v22, v16
	v_cvt_pk_fp8_f32 v18, v17, v16 op_sel:[0,0,1]
	v_mul_f32_e32 v19, v24, v50
	v_mul_f32_e32 v20, v25, v50
	v_mul_f32_e32 v21, v26, v50
	global_store_dword v[48:49], v18, off offset:8
	v_mov_b32_e32 v18, v97
	v_mul_f32_e32 v22, v27, v50
	v_mov_b32_e32 v36, v97
	v_mov_b32_e32 v25, v97
	v_mov_b32_e32 v26, v97
	v_mov_b32_e32 v27, v97
	s_waitcnt vmcnt(7)
	v_lshlrev_b32_e32 v23, 16, v224
	v_and_b32_e32 v16, 0xffff0000, v224
	v_mul_f32_e32 v19, v19, v23
	v_mul_f32_e32 v16, v20, v16
	v_cvt_pk_fp8_f32 v18, v19, v16
	v_lshlrev_b32_e32 v24, 16, v225
	v_and_b32_e32 v16, 0xffff0000, v225
	v_mul_f32_e32 v17, v21, v24
	v_mul_f32_e32 v16, v22, v16
	v_cvt_pk_fp8_f32 v18, v17, v16 op_sel:[0,0,1]
	v_mul_f32_e32 v19, v28, v50
	v_mul_f32_e32 v20, v29, v50
	v_mul_f32_e32 v21, v30, v50
	global_store_dword v[48:49], v18, off offset:16
	v_mov_b32_e32 v18, v97
	v_mul_f32_e32 v22, v31, v50
	v_mov_b32_e32 v28, v97
	v_mov_b32_e32 v29, v97
	v_mov_b32_e32 v30, v97
	v_mov_b32_e32 v31, v97
	s_waitcnt vmcnt(7)
	v_lshlrev_b32_e32 v23, 16, v226
	v_and_b32_e32 v16, 0xffff0000, v226
	v_mul_f32_e32 v19, v19, v23
	v_mul_f32_e32 v16, v20, v16
	v_cvt_pk_fp8_f32 v18, v19, v16
	v_lshlrev_b32_e32 v24, 16, v227
	v_and_b32_e32 v16, 0xffff0000, v227
	v_mul_f32_e32 v17, v21, v24
	v_mul_f32_e32 v16, v22, v16
	v_cvt_pk_fp8_f32 v18, v17, v16 op_sel:[0,0,1]
	v_mov_b32_e32 v21, v97
	v_mov_b32_e32 v22, v97
	v_mov_b32_e32 v23, v97
	global_store_dword v[48:49], v18, off offset:24
	v_mov_b32_e32 v18, v97
	v_mov_b32_e32 v24, v97
	s_waitcnt vmcnt(7)
	v_lshlrev_b32_e32 v19, 16, v228
	v_and_b32_e32 v16, 0xffff0000, v228
	v_mul_f32_e32 v0, v0, v19
	v_mul_f32_e32 v1, v1, v16
	v_cvt_pk_fp8_f32 v18, v0, v1
	v_lshlrev_b32_e32 v20, 16, v229
	v_and_b32_e32 v0, 0xffff0000, v229
	v_mul_f32_e32 v1, v2, v20
	v_mul_f32_e32 v0, v3, v0
	v_cvt_pk_fp8_f32 v18, v1, v0 op_sel:[0,0,1]
	v_mul_f32_e32 v3, v4, v50
	v_mul_f32_e32 v4, v5, v50
	v_mul_f32_e32 v5, v6, v50
	global_store_dword v[48:49], v18, off offset:32
	v_mul_f32_e32 v6, v7, v50
	v_mov_b32_e32 v2, v97
	v_mov_b32_e32 v17, v97
	v_mov_b32_e32 v18, v97
	v_mov_b32_e32 v19, v97
	v_mov_b32_e32 v20, v97
	s_waitcnt vmcnt(7)
	v_lshlrev_b32_e32 v7, 16, v230
	v_and_b32_e32 v0, 0xffff0000, v230
	v_mul_f32_e32 v3, v3, v7
	v_mul_f32_e32 v0, v4, v0
	v_cvt_pk_fp8_f32 v2, v3, v0
	v_lshlrev_b32_e32 v16, 16, v231
	v_and_b32_e32 v0, 0xffff0000, v231
	v_mul_f32_e32 v1, v5, v16
	v_mul_f32_e32 v0, v6, v0
	v_cvt_pk_fp8_f32 v2, v1, v0 op_sel:[0,0,1]
	v_mul_f32_e32 v3, v8, v50
	v_mul_f32_e32 v4, v9, v50
	v_mul_f32_e32 v5, v10, v50
	global_store_dword v[48:49], v2, off offset:40
	v_mov_b32_e32 v2, v97
	v_mul_f32_e32 v6, v11, v50
	v_mov_b32_e32 v16, v97
	s_waitcnt vmcnt(7)
	v_lshlrev_b32_e32 v7, 16, v232
	v_and_b32_e32 v0, 0xffff0000, v232
	v_mul_f32_e32 v3, v3, v7
	v_mul_f32_e32 v0, v4, v0
	v_cvt_pk_fp8_f32 v2, v3, v0
	v_lshlrev_b32_e32 v8, 16, v233
	v_and_b32_e32 v0, 0xffff0000, v233
	v_mul_f32_e32 v1, v5, v8
	v_mul_f32_e32 v0, v6, v0
	v_cvt_pk_fp8_f32 v2, v1, v0 op_sel:[0,0,1]
	v_mul_f32_e32 v3, v12, v50
	v_mul_f32_e32 v4, v13, v50
	v_mul_f32_e32 v5, v14, v50
	global_store_dword v[48:49], v2, off offset:48
	v_mov_b32_e32 v2, v97
	v_mul_f32_e32 v6, v15, v50
	v_mov_b32_e32 v34, v97
	v_mov_b32_e32 v35, v97
	s_waitcnt vmcnt(7)
	v_lshlrev_b32_e32 v7, 16, v234
	v_and_b32_e32 v0, 0xffff0000, v234
	v_mul_f32_e32 v3, v3, v7
	v_mul_f32_e32 v0, v4, v0
	v_cvt_pk_fp8_f32 v2, v3, v0
	v_lshlrev_b32_e32 v8, 16, v235
	v_and_b32_e32 v0, 0xffff0000, v235
	v_mul_f32_e32 v1, v5, v8
	v_mul_f32_e32 v0, v6, v0
	v_cvt_pk_fp8_f32 v2, v1, v0 op_sel:[0,0,1]
	global_store_dword v[48:49], v2, off offset:56

; __device__ __forceinline__ float bf_lo(unsigned u) { return __uint_as_float(u << 16); }
; __device__ __forceinline__ float bf_hi(unsigned u) { return __uint_as_float(u & 0xffff0000u); }
; __device__ __forceinline__ void moba_own_item(LAS unsigned char* lds, const Ptrs& P, int b, int h, int j) {
;     ...
;     const float inv = __builtin_amdgcn_rcpf(L);
; #pragma unroll
;     for (int dt = 0; dt < 4; ++dt)
; #pragma unroll
;         for (int g4 = 0; g4 < 4; ++g4) { const int d = 32 * dt + 8 * g4 + 4 * hi;
;             const u32x2 gw = *(const u32x2*)(P.PA() + qrow * NA + C_GA + h * 128 + d);
;             const float i64 = inv * 16.f; int w8 = 0;
;             w8 = __builtin_amdgcn_cvt_pk_fp8_f32(o[dt][4 * g4] * i64 * bf_lo(gw.x), o[dt][4 * g4 + 1] * i64 * bf_hi(gw.x), w8, false); w8 = __builtin_amdgcn_cvt_pk_fp8_f32(o[dt][4 * g4 + 2] * i64 * bf_lo(gw.y), o[dt][4 * g4 + 3] * i64 * bf_hi(gw.y), w8, true);
;             *(unsigned*)(P.Y8() + qrow * 2048 + h * 128 + d) = (unsigned)w8; }
.LBB0_1006:
	v_lshlrev_b32_e32 v0, 2, v166
	s_mov_b32 s29, s11
	v_lshl_add_u64 v[20:21], v[150:151], 0, s[28:29]
	v_lshlrev_b32_e32 v22, 1, v0
	v_mov_b32_e32 v23, v1
	v_lshl_add_u64 v[20:21], v[20:21], 0, v[22:23]
	v_add_co_u32_e32 v22, vcc, s56, v20
	v_rcp_f32_e32 v26, v46
	s_nop 0
	v_addc_co_u32_e32 v23, vcc, 0, v21, vcc
	global_load_dwordx2 v[204:205], v[22:23], off offset:2048
	global_load_dwordx2 v[206:207], v[22:23], off offset:2064
	global_load_dwordx2 v[208:209], v[22:23], off offset:2080
	global_load_dwordx2 v[210:211], v[22:23], off offset:2096
	global_load_dwordx2 v[212:213], v[22:23], off offset:2112
	global_load_dwordx2 v[214:215], v[22:23], off offset:2128
	global_load_dwordx2 v[216:217], v[22:23], off offset:2144
	global_load_dwordx2 v[218:219], v[22:23], off offset:2160
	global_load_dwordx2 v[220:221], v[22:23], off offset:2176
	global_load_dwordx2 v[222:223], v[22:23], off offset:2192
	global_load_dwordx2 v[224:225], v[22:23], off offset:2208
	global_load_dwordx2 v[226:227], v[22:23], off offset:2224
	global_load_dwordx2 v[228:229], v[22:23], off offset:2240
	global_load_dwordx2 v[230:231], v[22:23], off offset:2256
	global_load_dwordx2 v[232:233], v[22:23], off offset:2272
	global_load_dwordx2 v[234:235], v[22:23], off offset:2288
	v_mul_f32_e32 v26, 0x41800000, v26
	v_mul_f32_e32 v28, v90, v26
	v_mul_f32_e32 v29, v91, v26
	v_mov_b32_e32 v27, v1
	v_mul_f32_e32 v30, v88, v26
	v_mul_f32_e32 v31, v89, v26
	v_lshlrev_b64 v[24:25], 11, v[148:149]
	v_lshl_add_u64 v[24:25], s[24:25], 0, v[24:25]
	v_lshl_add_u64 v[24:25], v[24:25], 0, s[10:11]
	v_mul_f32_e32 v12, v12, v26
	v_mul_f32_e32 v13, v13, v26
	v_mul_f32_e32 v16, v16, v26
	v_mul_f32_e32 v17, v17, v26
	v_mul_f32_e32 v18, v18, v26
	v_mul_f32_e32 v19, v19, v26
	v_mul_f32_e32 v14, v14, v26
	v_mul_f32_e32 v15, v15, v26
	v_mul_f32_e32 v10, v10, v26
	v_mul_f32_e32 v11, v11, v26
	v_mul_f32_e32 v8, v8, v26
	v_mul_f32_e32 v9, v9, v26
	v_mul_f32_e32 v6, v6, v26
	v_mul_f32_e32 v7, v7, v26
	v_mul_f32_e32 v4, v4, v26
	v_mul_f32_e32 v5, v5, v26
	v_mul_f32_e32 v2, v2, v26
	v_mul_f32_e32 v3, v3, v26
	s_add_i32 s19, s19, s18
	s_cmpk_lt_i32 s19, 0x100
	s_waitcnt vmcnt(15)
	v_lshlrev_b32_e32 v46, 16, v204
	v_and_b32_e32 v22, 0xffff0000, v204
	v_mul_f32_e32 v28, v28, v46
	v_mul_f32_e32 v22, v29, v22
	v_cvt_pk_fp8_f32 v27, v28, v22
	v_lshlrev_b32_e32 v47, 16, v205
	v_and_b32_e32 v22, 0xffff0000, v205
	v_mul_f32_e32 v23, v30, v47
	v_mul_f32_e32 v22, v31, v22
	v_cvt_pk_fp8_f32 v27, v23, v22 op_sel:[0,0,1]
	v_lshl_add_u64 v[22:23], v[20:21], 0, s[26:27]
	v_lshl_add_u64 v[20:21], v[24:25], 0, v[0:1]
	v_mul_f32_e32 v28, v87, v26
	global_store_dword v[20:21], v27, off
	v_mul_f32_e32 v27, v86, v26
	v_mov_b32_e32 v0, v1
	v_mul_f32_e32 v29, v84, v26
	v_mul_f32_e32 v30, v85, v26
	s_waitcnt vmcnt(15)
	v_lshlrev_b32_e32 v31, 16, v206
	v_and_b32_e32 v24, 0xffff0000, v206
	v_mul_f32_e32 v27, v27, v31
	v_mul_f32_e32 v24, v28, v24
	v_cvt_pk_fp8_f32 v0, v27, v24
	v_lshlrev_b32_e32 v46, 16, v207
	v_and_b32_e32 v24, 0xffff0000, v207
	v_mul_f32_e32 v25, v29, v46
	v_mul_f32_e32 v24, v30, v24
	v_cvt_pk_fp8_f32 v0, v25, v24 op_sel:[0,0,1]
	v_mul_f32_e32 v27, v82, v26
	v_mul_f32_e32 v28, v83, v26
	v_mul_f32_e32 v29, v80, v26
	global_store_dword v[20:21], v0, off offset:8
	v_mov_b32_e32 v0, v1
	v_mul_f32_e32 v30, v81, v26
	s_waitcnt vmcnt(15)
	v_lshlrev_b32_e32 v31, 16, v208
	v_and_b32_e32 v24, 0xffff0000, v208
	v_mul_f32_e32 v27, v27, v31
	v_mul_f32_e32 v24, v28, v24
	v_cvt_pk_fp8_f32 v0, v27, v24
	v_lshlrev_b32_e32 v46, 16, v209
	v_and_b32_e32 v24, 0xffff0000, v209
	v_mul_f32_e32 v25, v29, v46
	v_mul_f32_e32 v24, v30, v24
	v_cvt_pk_fp8_f32 v0, v25, v24 op_sel:[0,0,1]
	v_mul_f32_e32 v27, v60, v26
	v_mul_f32_e32 v28, v61, v26
	v_mul_f32_e32 v29, v62, v26
	global_store_dword v[20:21], v0, off offset:16
	v_mov_b32_e32 v0, v1
	v_mul_f32_e32 v30, v63, v26
	s_waitcnt vmcnt(15)
	v_lshlrev_b32_e32 v31, 16, v210
	v_and_b32_e32 v24, 0xffff0000, v210
	v_mul_f32_e32 v27, v27, v31
	v_mul_f32_e32 v24, v28, v24
	v_cvt_pk_fp8_f32 v0, v27, v24
	v_lshlrev_b32_e32 v46, 16, v211
	v_and_b32_e32 v24, 0xffff0000, v211
	v_mul_f32_e32 v25, v29, v46
	v_mul_f32_e32 v24, v30, v24
	v_cvt_pk_fp8_f32 v0, v25, v24 op_sel:[0,0,1]
	v_mul_f32_e32 v27, v64, v26
	v_mul_f32_e32 v28, v65, v26
	v_mul_f32_e32 v29, v66, v26
	global_store_dword v[20:21], v0, off offset:24
	v_mov_b32_e32 v0, v1
	v_mul_f32_e32 v30, v67, v26
	s_waitcnt vmcnt(15)
	v_lshlrev_b32_e32 v31, 16, v212
	v_and_b32_e32 v24, 0xffff0000, v212
	v_mul_f32_e32 v27, v27, v31
	v_mul_f32_e32 v24, v28, v24
	v_cvt_pk_fp8_f32 v0, v27, v24
	v_lshlrev_b32_e32 v46, 16, v213
	v_and_b32_e32 v24, 0xffff0000, v213
	v_mul_f32_e32 v25, v29, v46
	v_mul_f32_e32 v24, v30, v24
	v_cvt_pk_fp8_f32 v0, v25, v24 op_sel:[0,0,1]
	v_mul_f32_e32 v27, v58, v26
	v_mul_f32_e32 v28, v59, v26
	v_mul_f32_e32 v29, v56, v26
	global_store_dword v[20:21], v0, off offset:32
	v_mov_b32_e32 v0, v1
	v_mul_f32_e32 v30, v57, v26
	s_waitcnt vmcnt(15)
; __device__ __forceinline__ float bf_lo(unsigned u) { return __uint_as_float(u << 16); }
; __device__ __forceinline__ float bf_hi(unsigned u) { return __uint_as_float(u & 0xffff0000u); }
; __device__ __forceinline__ void moba_own_item(LAS unsigned char* lds, const Ptrs& P, int b, int h, int j) {
;     ...
;     const float inv = __builtin_amdgcn_rcpf(L);
; #pragma unroll
;     for (int dt = 0; dt < 4; ++dt)
; #pragma unroll
;         for (int g4 = 0; g4 < 4; ++g4) { const int d = 32 * dt + 8 * g4 + 4 * hi;
;             const u32x2 gw = *(const u32x2*)(P.PA() + qrow * NA + C_GA + h * 128 + d);
;             const float i64 = inv * 16.f; int w8 = 0;
;             w8 = __builtin_amdgcn_cvt_pk_fp8_f32(o[dt][4 * g4] * i64 * bf_lo(gw.x), o[dt][4 * g4 + 1] * i64 * bf_hi(gw.x), w8, false); w8 = __builtin_amdgcn_cvt_pk_fp8_f32(o[dt][4 * g4 + 2] * i64 * bf_lo(gw.y), o[dt][4 * g4 + 3] * i64 * bf_hi(gw.y), w8, true);
;             *(unsigned*)(P.Y8() + qrow * 2048 + h * 128 + d) = (unsigned)w8; }
	v_lshlrev_b32_e32 v31, 16, v214
	v_and_b32_e32 v24, 0xffff0000, v214
	v_mul_f32_e32 v27, v27, v31
	v_mul_f32_e32 v24, v28, v24
	v_cvt_pk_fp8_f32 v0, v27, v24
	v_lshlrev_b32_e32 v46, 16, v215
	v_and_b32_e32 v24, 0xffff0000, v215
	v_mul_f32_e32 v25, v29, v46
	v_mul_f32_e32 v24, v30, v24
	v_cvt_pk_fp8_f32 v0, v25, v24 op_sel:[0,0,1]
	v_mul_f32_e32 v27, v54, v26
	v_mul_f32_e32 v28, v55, v26
	v_mul_f32_e32 v29, v52, v26
	global_store_dword v[20:21], v0, off offset:40
	v_mov_b32_e32 v0, v1
	v_mul_f32_e32 v30, v53, v26
	s_waitcnt vmcnt(15)
	v_lshlrev_b32_e32 v31, 16, v216
	v_and_b32_e32 v24, 0xffff0000, v216
	v_mul_f32_e32 v27, v27, v31
	v_mul_f32_e32 v24, v28, v24
	v_cvt_pk_fp8_f32 v0, v27, v24
	v_lshlrev_b32_e32 v46, 16, v217
	v_and_b32_e32 v24, 0xffff0000, v217
	v_mul_f32_e32 v25, v29, v46
	v_mul_f32_e32 v24, v30, v24
	v_cvt_pk_fp8_f32 v0, v25, v24 op_sel:[0,0,1]
	v_mul_f32_e32 v27, v50, v26
	v_mul_f32_e32 v28, v51, v26
	v_mul_f32_e32 v29, v48, v26
	global_store_dword v[20:21], v0, off offset:48
	v_mov_b32_e32 v0, v1
	v_mul_f32_e32 v30, v49, v26
	s_waitcnt vmcnt(15)
	v_lshlrev_b32_e32 v31, 16, v218
	v_and_b32_e32 v24, 0xffff0000, v218
	v_mul_f32_e32 v27, v27, v31
	v_mul_f32_e32 v24, v28, v24
	v_cvt_pk_fp8_f32 v0, v27, v24
	v_lshlrev_b32_e32 v46, 16, v219
	v_and_b32_e32 v24, 0xffff0000, v219
	v_mul_f32_e32 v25, v29, v46
	v_mul_f32_e32 v24, v30, v24
	v_cvt_pk_fp8_f32 v0, v25, v24 op_sel:[0,0,1]
	v_mul_f32_e32 v27, v32, v26
	v_mul_f32_e32 v28, v33, v26
	v_mul_f32_e32 v29, v34, v26
	global_store_dword v[20:21], v0, off offset:56
	v_mov_b32_e32 v0, v1
	v_mul_f32_e32 v30, v35, v26
	s_waitcnt vmcnt(15)
	v_lshlrev_b32_e32 v31, 16, v220
	v_and_b32_e32 v24, 0xffff0000, v220
	v_mul_f32_e32 v27, v27, v31
	v_mul_f32_e32 v24, v28, v24
	v_cvt_pk_fp8_f32 v0, v27, v24
	v_lshlrev_b32_e32 v32, 16, v221
	v_and_b32_e32 v24, 0xffff0000, v221
	v_mul_f32_e32 v25, v29, v32
	v_mul_f32_e32 v24, v30, v24
	v_cvt_pk_fp8_f32 v0, v25, v24 op_sel:[0,0,1]
	v_mul_f32_e32 v27, v36, v26
	v_mul_f32_e32 v28, v37, v26
	v_mul_f32_e32 v29, v38, v26
	global_store_dword v[20:21], v0, off offset:64
	v_mov_b32_e32 v0, v1
	v_mul_f32_e32 v30, v39, v26
	s_waitcnt vmcnt(15)
	v_lshlrev_b32_e32 v31, 16, v222
	v_and_b32_e32 v24, 0xffff0000, v222
	v_mul_f32_e32 v27, v27, v31
	v_mul_f32_e32 v24, v28, v24
	v_cvt_pk_fp8_f32 v0, v27, v24
	v_lshlrev_b32_e32 v32, 16, v223
	v_and_b32_e32 v24, 0xffff0000, v223
	v_mul_f32_e32 v25, v29, v32
	v_mul_f32_e32 v24, v30, v24
	v_cvt_pk_fp8_f32 v0, v25, v24 op_sel:[0,0,1]
	v_mul_f32_e32 v27, v40, v26
	v_mul_f32_e32 v28, v41, v26
	v_mul_f32_e32 v29, v42, v26
	global_store_dword v[20:21], v0, off offset:72
	v_mov_b32_e32 v0, v1
	v_mul_f32_e32 v30, v43, v26
	s_waitcnt vmcnt(15)
	v_lshlrev_b32_e32 v31, 16, v224
	v_and_b32_e32 v24, 0xffff0000, v224
	v_mul_f32_e32 v27, v27, v31
	v_mul_f32_e32 v24, v28, v24
	v_cvt_pk_fp8_f32 v0, v27, v24
	v_lshlrev_b32_e32 v32, 16, v225
	v_and_b32_e32 v24, 0xffff0000, v225
	v_mul_f32_e32 v25, v29, v32
	v_mul_f32_e32 v24, v30, v24
	v_cvt_pk_fp8_f32 v0, v25, v24 op_sel:[0,0,1]
	v_mul_f32_e32 v27, v44, v26
	v_mul_f32_e32 v28, v45, v26
	global_store_dword v[20:21], v0, off offset:80
	v_mov_b32_e32 v0, v1
	s_waitcnt vmcnt(15)
	v_lshlrev_b32_e32 v29, 16, v226
	v_and_b32_e32 v24, 0xffff0000, v226
	v_mul_f32_e32 v27, v27, v29
	v_mul_f32_e32 v24, v28, v24
	v_cvt_pk_fp8_f32 v0, v27, v24
	v_lshlrev_b32_e32 v30, 16, v227
	v_and_b32_e32 v24, 0xffff0000, v227
	v_mul_f32_e32 v12, v12, v30
	v_mul_f32_e32 v13, v13, v24
	v_cvt_pk_fp8_f32 v0, v12, v13 op_sel:[0,0,1]
	global_store_dword v[20:21], v0, off offset:88
	v_mov_b32_e32 v0, v1
	s_waitcnt vmcnt(15)
	v_lshlrev_b32_e32 v24, 16, v228
	v_and_b32_e32 v12, 0xffff0000, v228
	v_mul_f32_e32 v16, v16, v24
	v_mul_f32_e32 v12, v17, v12
	v_cvt_pk_fp8_f32 v0, v16, v12
	v_lshlrev_b32_e32 v25, 16, v229
	v_and_b32_e32 v12, 0xffff0000, v229
	v_mul_f32_e32 v13, v18, v25
	v_mul_f32_e32 v12, v19, v12
	v_cvt_pk_fp8_f32 v0, v13, v12 op_sel:[0,0,1]
	global_store_dword v[20:21], v0, off offset:96
	v_mov_b32_e32 v0, v1
	s_waitcnt vmcnt(15)
	v_lshlrev_b32_e32 v16, 16, v230
	v_and_b32_e32 v12, 0xffff0000, v230
	v_mul_f32_e32 v14, v14, v16
	v_mul_f32_e32 v12, v15, v12
	v_cvt_pk_fp8_f32 v0, v14, v12
	v_lshlrev_b32_e32 v17, 16, v231
	v_and_b32_e32 v12, 0xffff0000, v231
	v_mul_f32_e32 v10, v10, v17
	v_mul_f32_e32 v11, v11, v12
	v_cvt_pk_fp8_f32 v0, v10, v11 op_sel:[0,0,1]
	global_store_dword v[20:21], v0, off offset:104
	v_mov_b32_e32 v0, v1
	s_waitcnt vmcnt(15)
	v_lshlrev_b32_e32 v12, 16, v232
	v_and_b32_e32 v10, 0xffff0000, v232
	v_mul_f32_e32 v8, v8, v12
	v_mul_f32_e32 v9, v9, v10
	v_cvt_pk_fp8_f32 v0, v8, v9
	v_lshlrev_b32_e32 v13, 16, v233
	v_and_b32_e32 v8, 0xffff0000, v233
	v_mul_f32_e32 v6, v6, v13
	v_mul_f32_e32 v7, v7, v8
	v_cvt_pk_fp8_f32 v0, v6, v7 op_sel:[0,0,1]
	global_store_dword v[20:21], v0, off offset:112
	v_mov_b32_e32 v0, v1
	s_waitcnt vmcnt(15)
	v_lshlrev_b32_e32 v8, 16, v234
	v_and_b32_e32 v6, 0xffff0000, v234
	v_mul_f32_e32 v4, v4, v8
	v_mul_f32_e32 v5, v5, v6
	v_cvt_pk_fp8_f32 v0, v4, v5
	v_lshlrev_b32_e32 v9, 16, v235
	v_and_b32_e32 v4, 0xffff0000, v235
	v_mul_f32_e32 v2, v2, v9
	v_mul_f32_e32 v3, v3, v4
	v_cvt_pk_fp8_f32 v0, v2, v3 op_sel:[0,0,1]
	global_store_dword v[20:21], v0, off offset:120
	s_barrier
	s_cbranch_scc0 .LBB0_1038

; #define PHASE_BEGIN() P.reload(launder_s(kargs)); const int G = sopq(G0), bx = sopq(bx0); const int lane = opq(lane_id()); const int gw = bx * 8 + wave, NGW = G * 8; (void)gw; (void)NGW; (void)lane
; #define PHASE_BEGIN() P.reload(launder_s(kargs)); const int G = sopq(G0), bx = sopq(bx0); const int lane = opq(lane_id()); const int gw = bx * 8 + wave, NGW = G * 8; (void)gw; (void)NGW; (void)lane
; __global__ void __launch_bounds__(NTHR, 2) fwd_kernel(Args args) {
;     ...
;     if (IN(17)) {
;         PHASE_BEGIN();
;         for (int mrow = gw; mrow < M; mrow += NGW) {
;             const float rs = rsqrtf(P.SSQ()[(size_t)4 * M + mrow] * (1.f / DM) + EPS);
;             f32x4* xr = (f32x4*)(P.out + (size_t)mrow * DM) + lane; const f32x4* gr = (const f32x4*)P.fin_g + lane;
; #pragma unroll
;             for (int jv = 0; jv < 8; ++jv) { const f32x4 v = xr[64 * jv], gg = gr[64 * jv]; xr[64 * jv] = v * rs * gg; }
;         }
;     }
.LBB0_2277:
	v_readlane_b32 s0, v254, 0
	v_readlane_b32 s2, v254, 2
	v_readlane_b32 s1, v254, 1
	v_readlane_b32 s3, v254, 3
	s_cmp_gt_i32 s2, 17
	s_cselect_b64 s[0:1], -1, 0
	s_xor_b64 s[2:3], s[44:45], -1
	s_or_b64 s[0:1], s[0:1], s[2:3]
	s_and_b64 vcc, exec, s[0:1]
	s_cbranch_vccnz .LBB0_2281
	v_readlane_b32 s0, v254, 7
	v_readlane_b32 s1, v254, 8
	s_waitcnt vmcnt(0)
	v_mbcnt_lo_u32_b32 v0, -1, 0
	v_writelane_b32 v254, s0, 7
	v_mbcnt_hi_u32_b32 v0, -1, v0
	s_nop 0
	v_writelane_b32 v254, s1, 8
	s_nop 0
	v_readlane_b32 s0, v254, 4
	v_readlane_b32 s1, v254, 5
	s_nop 0
	v_writelane_b32 v254, s0, 4
	s_nop 1
	v_writelane_b32 v254, s1, 5
	s_lshl_b32 s0, s79, 3
	v_readlane_b32 s1, v254, 15
	s_add_i32 s0, s0, s1
	s_cmpk_gt_i32 s0, 0x3fff
	s_cbranch_scc1 .LBB0_2281
	v_readlane_b32 s2, v254, 7
	v_readlane_b32 s3, v254, 8
	s_waitcnt lgkmcnt(0)
	s_load_dwordx4 s[8:11], s[2:3], 0x90
	s_load_dwordx2 s[4:5], s[2:3], 0xa0
	v_ashrrev_i32_e32 v1, 31, v0
	v_lshlrev_b64 v[10:11], 4, v[0:1]
	s_mov_b64 s[6:7], 0x1400
	s_waitcnt lgkmcnt(0)
	v_lshl_add_u64 v[0:1], s[8:9], 0, v[10:11]
	v_lshl_add_u64 v[4:5], v[0:1], 0, s[6:7]
	s_mov_b64 s[6:7], 0x1800
	v_readlane_b32 s2, v254, 4
	v_lshl_add_u64 v[6:7], v[0:1], 0, s[6:7]
	s_mov_b64 s[6:7], 0x1c00
	s_ashr_i32 s1, s0, 31
	v_readlane_b32 s3, v254, 5
	s_lshl_b32 s2, s2, 3
	v_lshl_add_u64 v[8:9], v[0:1], 0, s[6:7]
	s_lshl_b64 s[6:7], s[0:1], 2
	s_add_u32 s3, s4, s6
	s_addc_u32 s5, s5, s7
	s_add_u32 s4, s3, 0x32f40000
	s_addc_u32 s5, s5, 0
	s_ashr_i32 s3, s2, 31
	s_lshl_b64 s[6:7], s[2:3], 2
	s_lshl_b64 s[12:13], s[0:1], 13
	s_add_u32 s10, s10, s12
	s_addc_u32 s11, s11, s13
	s_mov_b64 s[8:9], 0x1000
	v_lshl_add_u64 v[10:11], s[10:11], 0, v[10:11]
	v_lshl_add_u64 v[2:3], v[0:1], 0, s[8:9]
	v_lshl_add_u64 v[10:11], v[10:11], 0, s[8:9]
	s_lshl_b64 s[8:9], s[2:3], 13
	v_mov_b32_e32 v12, 0
	v_mov_b32_e32 v13, 0x358637bd
	s_mov_b32 s1, 0x800000
	global_load_dwordx4 v[60:63], v[0:1], off
	global_load_dwordx4 v[64:67], v[0:1], off offset:1024
	global_load_dwordx4 v[68:71], v[0:1], off offset:2048
	global_load_dwordx4 v[72:75], v[0:1], off offset:3072
	global_load_dwordx4 v[76:79], v[2:3], off
	global_load_dwordx4 v[80:83], v[4:5], off
	global_load_dwordx4 v[84:87], v[6:7], off
	global_load_dwordx4 v[88:91], v[8:9], off
.LBB0_2280:
	global_load_dword v26, v12, s[4:5]
	global_load_dwordx4 v[28:31], v[10:11], off offset:-4096
	global_load_dwordx4 v[32:35], v[10:11], off offset:-3072
	global_load_dwordx4 v[36:39], v[10:11], off offset:-2048
	global_load_dwordx4 v[40:43], v[10:11], off offset:-1024
	global_load_dwordx4 v[44:47], v[10:11], off
	global_load_dwordx4 v[48:51], v[10:11], off offset:1024
	global_load_dwordx4 v[52:55], v[10:11], off offset:2048
	global_load_dwordx4 v[56:59], v[10:11], off offset:3072
	s_add_i32 s0, s0, s2
	s_add_u32 s4, s4, s6
	s_addc_u32 s5, s5, s7
	s_waitcnt vmcnt(8)
	v_fmamk_f32 v26, v26, 0x3a000000, v13
	v_mul_f32_e32 v27, 0x4b800000, v26
	v_cmp_gt_f32_e32 vcc, s1, v26
	s_nop 1
	v_cndmask_b32_e32 v26, v26, v27, vcc
	v_rsq_f32_e32 v26, v26
	s_nop 0
	v_mul_f32_e32 v27, 0x45800000, v26
	v_cndmask_b32_e32 v26, v26, v27, vcc
	s_waitcnt vmcnt(7)
	v_pk_mul_f32 v[28:29], v[26:27], v[28:29] op_sel_hi:[0,1]
	v_pk_mul_f32 v[30:31], v[26:27], v[30:31] op_sel_hi:[0,1]
	v_pk_mul_f32 v[30:31], v[30:31], v[62:63]
	v_pk_mul_f32 v[28:29], v[28:29], v[60:61]
	global_store_dwordx4 v[10:11], v[28:31], off offset:-4096
	s_waitcnt vmcnt(7)
	v_pk_mul_f32 v[32:33], v[26:27], v[32:33] op_sel_hi:[0,1]
	v_pk_mul_f32 v[34:35], v[26:27], v[34:35] op_sel_hi:[0,1]
	v_pk_mul_f32 v[34:35], v[34:35], v[66:67]
	v_pk_mul_f32 v[32:33], v[32:33], v[64:65]
	global_store_dwordx4 v[10:11], v[32:35], off offset:-3072
	s_waitcnt vmcnt(7)
	v_pk_mul_f32 v[36:37], v[26:27], v[36:37] op_sel_hi:[0,1]
	v_pk_mul_f32 v[38:39], v[26:27], v[38:39] op_sel_hi:[0,1]
	v_pk_mul_f32 v[38:39], v[38:39], v[70:71]
	v_pk_mul_f32 v[36:37], v[36:37], v[68:69]
	global_store_dwordx4 v[10:11], v[36:39], off offset:-2048
	s_waitcnt vmcnt(7)
	v_pk_mul_f32 v[40:41], v[26:27], v[40:41] op_sel_hi:[0,1]
	v_pk_mul_f32 v[42:43], v[26:27], v[42:43] op_sel_hi:[0,1]
	v_pk_mul_f32 v[42:43], v[42:43], v[74:75]
	v_pk_mul_f32 v[40:41], v[40:41], v[72:73]
	global_store_dwordx4 v[10:11], v[40:43], off offset:-1024
	s_waitcnt vmcnt(7)
	v_pk_mul_f32 v[44:45], v[26:27], v[44:45] op_sel_hi:[0,1]
	v_pk_mul_f32 v[46:47], v[26:27], v[46:47] op_sel_hi:[0,1]
	v_pk_mul_f32 v[46:47], v[46:47], v[78:79]
	v_pk_mul_f32 v[44:45], v[44:45], v[76:77]
	global_store_dwordx4 v[10:11], v[44:47], off
	s_waitcnt vmcnt(7)
	v_pk_mul_f32 v[48:49], v[26:27], v[48:49] op_sel_hi:[0,1]
	v_pk_mul_f32 v[50:51], v[26:27], v[50:51] op_sel_hi:[0,1]
	v_pk_mul_f32 v[50:51], v[50:51], v[82:83]
	v_pk_mul_f32 v[48:49], v[48:49], v[80:81]
	global_store_dwordx4 v[10:11], v[48:51], off offset:1024
	s_waitcnt vmcnt(7)
	v_pk_mul_f32 v[52:53], v[26:27], v[52:53] op_sel_hi:[0,1]
	v_pk_mul_f32 v[54:55], v[26:27], v[54:55] op_sel_hi:[0,1]
	v_pk_mul_f32 v[54:55], v[54:55], v[86:87]
	v_pk_mul_f32 v[52:53], v[52:53], v[84:85]
	global_store_dwordx4 v[10:11], v[52:55], off offset:2048
	s_waitcnt vmcnt(7)
	v_pk_mul_f32 v[56:57], v[26:27], v[56:57] op_sel_hi:[0,1]
	v_pk_mul_f32 v[58:59], v[26:27], v[58:59] op_sel_hi:[0,1]
	v_pk_mul_f32 v[58:59], v[58:59], v[90:91]
	v_pk_mul_f32 v[56:57], v[56:57], v[88:89]
	global_store_dwordx4 v[10:11], v[56:59], off offset:3072
	v_lshl_add_u64 v[10:11], v[10:11], 0, s[8:9]
	s_cmpk_lt_i32 s0, 0x4000
	s_cbranch_scc1 .LBB0_2280
